# la_prep runs on waves 0-3 only (twice the passes) so the S5 first-pass scan on waves 4-7 starts at phase entry
# baseline (speedup 1.0000x reference)
; __device__ __forceinline__ int tidx() { int t = threadIdx.x; asm volatile("" : "+v"(t)); return t; }
; __device__ __forceinline__ int bidx() { int b = blockIdx.x; asm volatile("" : "+s"(b)); return b; }
; __device__ __forceinline__ void la_prep(const Params& p, int l) {
;     const float* ZR = (const float*)(p.ws + WS_ZR); bf16_t* LA = (bf16_t*)(p.ws + WS_LA); const float* mu = p.in[7] + l * RWC;
;     for (int idx = bidx() * 512 + tidx(); idx < MT * 64; idx += gridDim.x * 512) {
;         const int m = idx >> 6, c4 = (idx & 63) * 4; const int col = 2304 + c4;
.LBB0_359:
	s_andn2_b64 vcc, exec, s[4:5]
	v_readlane_b32 s4, v254, 31
	v_readlane_b32 s5, v254, 32
	s_cbranch_vccnz .LBB0_425
	s_mov_b32 s6, s2
	v_mov_b32_e32 v0, v182
	s_mov_b32 s4, 0x80000
	v_lshl_add_u32 v10, s6, 8, v0
	v_mov_b32_e32 v1, s4
	v_cmp_lt_u32_e32 vcc, 0xff, v0
	s_nop 1
	v_cndmask_b32_e32 v10, v10, v1, vcc
	v_cmp_gt_i32_e32 vcc, s4, v10
	s_and_saveexec_b64 s[4:5], vcc
	s_cbranch_execz .LBB0_387
	v_lshlrev_b32_e32 v0, 2, v0
	v_lshl_add_u32 v11, s6, 10, v0
	s_mov_b64 s[6:7], 0
	s_branch .LBB0_364

; __device__ __forceinline__ int tidx() { int t = threadIdx.x; asm volatile("" : "+v"(t)); return t; }
; __device__ __forceinline__ int bidx() { int b = blockIdx.x; asm volatile("" : "+s"(b)); return b; }
; __device__ __forceinline__ unsigned cvt_pk_bf16(float lo, float hi) { unsigned r; asm volatile("v_cvt_pk_bf16_f32 %0, %1, %2" : "=v"(r) : "v"(lo), "v"(hi)); return r; }
; __device__ __forceinline__ float sigmoidf_(float x) { return __builtin_amdgcn_rcpf(1.0f + __expf(-x)); }
; __device__ __forceinline__ void la_prep(const Params& p, int l) {
;     ...
;     for (int idx = bidx() * 512 + tidx(); idx < MT * 64; idx += gridDim.x * 512) {
;         const int m = idx >> 6, c4 = (idx & 63) * 4; const int col = 2304 + c4;
;         const f32x4 zc = *(const f32x4*)(ZR + (size_t)m * RWC + col);
;         f32x4 zp = {0.f, 0.f, 0.f, 0.f}; if (m & (SEQ - 1)) zp = *(const f32x4*)(ZR + (size_t)(m - 1) * RWC + col);
;         const f32x4 m4 = *(const f32x4*)(mu + col);
;         f32x4 z = zc + (zp - zc) * m4;
;         if (c4 < 64) { z.x = tanhf(z.x); z.y = tanhf(z.y); z.z = tanhf(z.z); z.w = tanhf(z.w); }
;         else if (c4 >= 128) { z.x = sigmoidf_(z.x); z.y = sigmoidf_(z.y); z.z = sigmoidf_(z.z); z.w = sigmoidf_(z.w); }
;         u32x2 w; w.x = cvt_pk_bf16(z.x, z.y); w.y = cvt_pk_bf16(z.z, z.w);
;         *(u32x2*)(LA + (size_t)m * 256 + c4) = w;
.LBB0_363:
	s_or_b64 exec, exec, s[8:9]
	v_readlane_b32 s8, v251, 22
	v_cvt_pk_bf16_f32 v0, v0, v1
	v_cvt_pk_bf16_f32 v1, v2, v3
	v_lshlrev_b64 v[2:3], 9, v[8:9]
	v_readlane_b32 s9, v251, 23
	v_lshlrev_b32_e32 v136, 1, v12
	v_readlane_b32 s3, v252, 46
	v_lshl_add_u64 v[2:3], s[8:9], 0, v[2:3]
	v_readlane_b32 s8, v252, 57
	v_lshl_add_u64 v[2:3], v[2:3], 0, v[136:137]
	s_lshr_b32 s3, s3, 1
	s_lshr_b32 s8, s8, 1
	s_nop 1
	v_add_u32_e32 v11, s3, v11
	v_add_u32_e32 v10, s8, v10
	s_mov_b32 s8, 0x7ffff
	v_cmp_lt_i32_e32 vcc, s8, v10
	s_or_b64 s[6:7], vcc, s[6:7]
	global_store_dwordx2 v[2:3], v[0:1], off
	v_readlane_b32 s9, v252, 58
	s_andn2_b64 exec, exec, s[6:7]
	s_cbranch_execz .LBB0_387
